# non-temporal hint on the write-once f32 k/v output stores of the in-proj epilogue
# baseline (speedup 1.0000x reference)
;     DI void operator()(const f32x4 (&acc)[2][2][4][2], const pg8::Unit& u, int wr, int wc, int fr, int fq) const {
;     ...
;                 const int R = u.pm * 256 + ai * 128 + wr * 64 + m * 16 + fr;
;                 float* fo = nullptr;
;                 if (iskv) {
;                     if (R < ROWS_P) { const int b = R / LPAD, t = R - b * LPAD; if (t < LP) fo = p.out + O_PAK + oi * PKV_SZ + ((size_t)b * LP + t) * 512 - seg * 512; }
;                     else fo = p.out + O_SAK + oi * SKV_SZ + (size_t)(R - ROWS_P) * 512 - seg * 512;
;                 }
;                 bf16_t* uo = p.u + (size_t)R * NU;
; #pragma unroll
;                 for (int bj = 0; bj < 2; ++bj) {
;                     const int n = colt + bj * 128 + wc * 32 + 8 * fq;
;                     f32x4 v0 = acc[ai][bj][m][0], v1 = acc[ai][bj][m][1];
;                     if (fo) { *(f32x4*)(fo + n) = v0; *(f32x4*)(fo + n + 4) = v1; }
.LBB0_157:
	v_lshl_or_b32 v158, s0, 8, v179
	v_cmp_ne_u64_e64 s[0:1], 0, v[162:163]
	v_ashrrev_i32_e32 v159, 31, v158
	s_and_saveexec_b64 s[6:7], s[0:1]
	s_cbranch_execz .LBB0_159
	v_lshl_add_u64 v[130:131], v[158:159], 2, v[162:163]
	global_store_dwordx4 v[130:131], v[126:129], off
	global_store_dwordx4 v[130:131], v[122:125], off offset:16 nt

; DI unsigned pk2(float a, float b) { f32x2 v = {a, b}; bf16x2v r = __builtin_convertvector(v, bf16x2v); return __builtin_bit_cast(unsigned, r); }
;     DI void operator()(const f32x4 (&acc)[2][2][4][2], const pg8::Unit& u, int wr, int wc, int fr, int fq) const {
;     ...
;                 bf16_t* uo = p.u + (size_t)R * NU;
; #pragma unroll
;                 for (int bj = 0; bj < 2; ++bj) {
;                     const int n = colt + bj * 128 + wc * 32 + 8 * fq;
;                     f32x4 v0 = acc[ai][bj][m][0], v1 = acc[ai][bj][m][1];
;                     if (fo) { *(f32x4*)(fo + n) = v0; *(f32x4*)(fo + n + 4) = v1; }
;                     if (isq) { v0 = v0 * QSCALE; v1 = v1 * QSCALE; }
;                     else if (isg) {
; #pragma unroll
;                         for (int j = 0; j < 4; ++j) { v0[j] = v0[j] / (1.0f + __expf(-v0[j])); v1[j] = v1[j] / (1.0f + __expf(-v1[j])); }
;                     }
;                     *(u32x4*)(uo + n) = (u32x4){pk2(v0[0], v0[1]), pk2(v0[2], v0[3]), pk2(v1[0], v1[1]), pk2(v1[2], v1[3])};
.LBB0_165:
	v_ashrrev_i32_e32 v161, 31, v160
	v_lshlrev_b64 v[122:123], 13, v[160:161]
	v_lshl_add_u64 v[126:127], s[68:69], 0, v[122:123]
	v_cvt_pk_bf16_f32 v122, v130, v131
	v_cvt_pk_bf16_f32 v123, v132, v133
	v_cvt_pk_bf16_f32 v124, v134, v135
	v_cvt_pk_bf16_f32 v125, v136, v137
	v_lshl_add_u64 v[130:131], v[158:159], 1, v[126:127]
	global_store_dwordx4 v[130:131], v[122:125], off
	s_and_saveexec_b64 s[36:37], s[0:1]
	s_cbranch_execz .LBB0_167
	v_lshl_add_u64 v[122:123], v[158:159], 2, v[162:163]
	global_store_dwordx4 v[122:123], v[118:121], off offset:512 nt
	global_store_dwordx4 v[122:123], v[114:117], off offset:528 nt

;     DI void operator()(const f32x4 (&acc)[2][2][4][2], const pg8::Unit& u, int wr, int wc, int fr, int fq) const {
;     ...
;                 for (int bj = 0; bj < 2; ++bj) {
;                     const int n = colt + bj * 128 + wc * 32 + 8 * fq;
;                     f32x4 v0 = acc[ai][bj][m][0], v1 = acc[ai][bj][m][1];
;                     if (fo) { *(f32x4*)(fo + n) = v0; *(f32x4*)(fo + n + 4) = v1; }
.LBB0_182:
	global_store_dwordx4 v[124:125], v[110:113], off
	global_store_dwordx4 v[124:125], v[106:109], off offset:16 nt

; DI unsigned pk2(float a, float b) { f32x2 v = {a, b}; bf16x2v r = __builtin_convertvector(v, bf16x2v); return __builtin_bit_cast(unsigned, r); }
;     DI void operator()(const f32x4 (&acc)[2][2][4][2], const pg8::Unit& u, int wr, int wc, int fr, int fq) const {
;     ...
;                 bf16_t* uo = p.u + (size_t)R * NU;
; #pragma unroll
;                 for (int bj = 0; bj < 2; ++bj) {
;                     const int n = colt + bj * 128 + wc * 32 + 8 * fq;
;                     f32x4 v0 = acc[ai][bj][m][0], v1 = acc[ai][bj][m][1];
;                     if (fo) { *(f32x4*)(fo + n) = v0; *(f32x4*)(fo + n + 4) = v1; }
;                     if (isq) { v0 = v0 * QSCALE; v1 = v1 * QSCALE; }
;                     else if (isg) {
; #pragma unroll
;                         for (int j = 0; j < 4; ++j) { v0[j] = v0[j] / (1.0f + __expf(-v0[j])); v1[j] = v1[j] / (1.0f + __expf(-v1[j])); }
;                     }
;                     *(u32x4*)(uo + n) = (u32x4){pk2(v0[0], v0[1]), pk2(v0[2], v0[3]), pk2(v1[0], v1[1]), pk2(v1[2], v1[3])};
.LBB0_189:
	v_ashrrev_i32_e32 v123, 31, v122
	v_lshlrev_b64 v[106:107], 13, v[122:123]
	v_lshl_add_u64 v[110:111], s[68:69], 0, v[106:107]
	v_cvt_pk_bf16_f32 v106, v114, v115
	v_cvt_pk_bf16_f32 v107, v116, v117
	v_cvt_pk_bf16_f32 v108, v118, v119
	v_cvt_pk_bf16_f32 v109, v120, v121
	v_lshl_add_u64 v[114:115], v[158:159], 1, v[110:111]
	global_store_dwordx4 v[114:115], v[106:109], off
	s_and_saveexec_b64 s[36:37], s[0:1]
	s_cbranch_execz .LBB0_191
	global_store_dwordx4 v[124:125], v[102:105], off offset:512 nt
	global_store_dwordx4 v[124:125], v[98:101], off offset:528 nt

;     DI void operator()(const f32x4 (&acc)[2][2][4][2], const pg8::Unit& u, int wr, int wc, int fr, int fq) const {
;     ...
;                 for (int bj = 0; bj < 2; ++bj) {
;                     const int n = colt + bj * 128 + wc * 32 + 8 * fq;
;                     f32x4 v0 = acc[ai][bj][m][0], v1 = acc[ai][bj][m][1];
;                     if (fo) { *(f32x4*)(fo + n) = v0; *(f32x4*)(fo + n + 4) = v1; }
.LBB0_206:
	global_store_dwordx4 v[108:109], v[94:97], off
	global_store_dwordx4 v[108:109], v[90:93], off offset:16 nt

; DI unsigned pk2(float a, float b) { f32x2 v = {a, b}; bf16x2v r = __builtin_convertvector(v, bf16x2v); return __builtin_bit_cast(unsigned, r); }
;     DI void operator()(const f32x4 (&acc)[2][2][4][2], const pg8::Unit& u, int wr, int wc, int fr, int fq) const {
;     ...
;                 bf16_t* uo = p.u + (size_t)R * NU;
; #pragma unroll
;                 for (int bj = 0; bj < 2; ++bj) {
;                     const int n = colt + bj * 128 + wc * 32 + 8 * fq;
;                     f32x4 v0 = acc[ai][bj][m][0], v1 = acc[ai][bj][m][1];
;                     if (fo) { *(f32x4*)(fo + n) = v0; *(f32x4*)(fo + n + 4) = v1; }
;                     if (isq) { v0 = v0 * QSCALE; v1 = v1 * QSCALE; }
;                     else if (isg) {
; #pragma unroll
;                         for (int j = 0; j < 4; ++j) { v0[j] = v0[j] / (1.0f + __expf(-v0[j])); v1[j] = v1[j] / (1.0f + __expf(-v1[j])); }
;                     }
;                     *(u32x4*)(uo + n) = (u32x4){pk2(v0[0], v0[1]), pk2(v0[2], v0[3]), pk2(v1[0], v1[1]), pk2(v1[2], v1[3])};
.LBB0_213:
	v_ashrrev_i32_e32 v107, 31, v106
	v_lshlrev_b64 v[90:91], 13, v[106:107]
	v_lshl_add_u64 v[94:95], s[68:69], 0, v[90:91]
	v_cvt_pk_bf16_f32 v90, v98, v99
	v_cvt_pk_bf16_f32 v91, v100, v101
	v_cvt_pk_bf16_f32 v92, v102, v103
	v_cvt_pk_bf16_f32 v93, v104, v105
	v_lshl_add_u64 v[98:99], v[158:159], 1, v[94:95]
	global_store_dwordx4 v[98:99], v[90:93], off
	s_and_saveexec_b64 s[36:37], s[0:1]
	s_cbranch_execz .LBB0_215
	global_store_dwordx4 v[108:109], v[86:89], off offset:512 nt
	global_store_dwordx4 v[108:109], v[82:85], off offset:528 nt

;     DI void operator()(const f32x4 (&acc)[2][2][4][2], const pg8::Unit& u, int wr, int wc, int fr, int fq) const {
;     ...
;                 for (int bj = 0; bj < 2; ++bj) {
;                     const int n = colt + bj * 128 + wc * 32 + 8 * fq;
;                     f32x4 v0 = acc[ai][bj][m][0], v1 = acc[ai][bj][m][1];
;                     if (fo) { *(f32x4*)(fo + n) = v0; *(f32x4*)(fo + n + 4) = v1; }
.LBB0_230:
	global_store_dwordx4 v[92:93], v[78:81], off
	global_store_dwordx4 v[92:93], v[74:77], off offset:16 nt

; DI unsigned pk2(float a, float b) { f32x2 v = {a, b}; bf16x2v r = __builtin_convertvector(v, bf16x2v); return __builtin_bit_cast(unsigned, r); }
;     DI void operator()(const f32x4 (&acc)[2][2][4][2], const pg8::Unit& u, int wr, int wc, int fr, int fq) const {
;     ...
;                 bf16_t* uo = p.u + (size_t)R * NU;
; #pragma unroll
;                 for (int bj = 0; bj < 2; ++bj) {
;                     const int n = colt + bj * 128 + wc * 32 + 8 * fq;
;                     f32x4 v0 = acc[ai][bj][m][0], v1 = acc[ai][bj][m][1];
;                     if (fo) { *(f32x4*)(fo + n) = v0; *(f32x4*)(fo + n + 4) = v1; }
;                     if (isq) { v0 = v0 * QSCALE; v1 = v1 * QSCALE; }
;                     else if (isg) {
; #pragma unroll
;                         for (int j = 0; j < 4; ++j) { v0[j] = v0[j] / (1.0f + __expf(-v0[j])); v1[j] = v1[j] / (1.0f + __expf(-v1[j])); }
;                     }
;                     *(u32x4*)(uo + n) = (u32x4){pk2(v0[0], v0[1]), pk2(v0[2], v0[3]), pk2(v1[0], v1[1]), pk2(v1[2], v1[3])};
.LBB0_237:
	v_ashrrev_i32_e32 v91, 31, v90
	v_lshlrev_b64 v[74:75], 13, v[90:91]
	v_lshl_add_u64 v[78:79], s[68:69], 0, v[74:75]
	v_cvt_pk_bf16_f32 v74, v82, v83
	v_cvt_pk_bf16_f32 v75, v84, v85
	v_cvt_pk_bf16_f32 v76, v86, v87
	v_cvt_pk_bf16_f32 v77, v88, v89
	v_lshl_add_u64 v[82:83], v[158:159], 1, v[78:79]
	global_store_dwordx4 v[82:83], v[74:77], off
	s_and_saveexec_b64 s[36:37], s[0:1]
	s_cbranch_execz .LBB0_239
	global_store_dwordx4 v[92:93], v[70:73], off offset:512 nt
	global_store_dwordx4 v[92:93], v[66:69], off offset:528 nt

;     DI void operator()(const f32x4 (&acc)[2][2][4][2], const pg8::Unit& u, int wr, int wc, int fr, int fq) const {
;     ...
;                 for (int bj = 0; bj < 2; ++bj) {
;                     const int n = colt + bj * 128 + wc * 32 + 8 * fq;
;                     f32x4 v0 = acc[ai][bj][m][0], v1 = acc[ai][bj][m][1];
;                     if (fo) { *(f32x4*)(fo + n) = v0; *(f32x4*)(fo + n + 4) = v1; }
.LBB0_254:
	global_store_dwordx4 v[76:77], v[62:65], off
	global_store_dwordx4 v[76:77], v[58:61], off offset:16 nt

; DI unsigned pk2(float a, float b) { f32x2 v = {a, b}; bf16x2v r = __builtin_convertvector(v, bf16x2v); return __builtin_bit_cast(unsigned, r); }
;     DI void operator()(const f32x4 (&acc)[2][2][4][2], const pg8::Unit& u, int wr, int wc, int fr, int fq) const {
;     ...
;                 bf16_t* uo = p.u + (size_t)R * NU;
; #pragma unroll
;                 for (int bj = 0; bj < 2; ++bj) {
;                     const int n = colt + bj * 128 + wc * 32 + 8 * fq;
;                     f32x4 v0 = acc[ai][bj][m][0], v1 = acc[ai][bj][m][1];
;                     if (fo) { *(f32x4*)(fo + n) = v0; *(f32x4*)(fo + n + 4) = v1; }
;                     if (isq) { v0 = v0 * QSCALE; v1 = v1 * QSCALE; }
;                     else if (isg) {
; #pragma unroll
;                         for (int j = 0; j < 4; ++j) { v0[j] = v0[j] / (1.0f + __expf(-v0[j])); v1[j] = v1[j] / (1.0f + __expf(-v1[j])); }
;                     }
;                     *(u32x4*)(uo + n) = (u32x4){pk2(v0[0], v0[1]), pk2(v0[2], v0[3]), pk2(v1[0], v1[1]), pk2(v1[2], v1[3])};
.LBB0_261:
	v_ashrrev_i32_e32 v75, 31, v74
	v_lshlrev_b64 v[58:59], 13, v[74:75]
	v_lshl_add_u64 v[62:63], s[68:69], 0, v[58:59]
	v_cvt_pk_bf16_f32 v58, v66, v67
	v_cvt_pk_bf16_f32 v59, v68, v69
	v_cvt_pk_bf16_f32 v60, v70, v71
	v_cvt_pk_bf16_f32 v61, v72, v73
	v_lshl_add_u64 v[66:67], v[158:159], 1, v[62:63]
	global_store_dwordx4 v[66:67], v[58:61], off
	s_and_saveexec_b64 s[36:37], s[0:1]
	s_cbranch_execz .LBB0_263
	global_store_dwordx4 v[76:77], v[54:57], off offset:512 nt
	global_store_dwordx4 v[76:77], v[50:53], off offset:528 nt

;     DI void operator()(const f32x4 (&acc)[2][2][4][2], const pg8::Unit& u, int wr, int wc, int fr, int fq) const {
;     ...
;                 for (int bj = 0; bj < 2; ++bj) {
;                     const int n = colt + bj * 128 + wc * 32 + 8 * fq;
;                     f32x4 v0 = acc[ai][bj][m][0], v1 = acc[ai][bj][m][1];
;                     if (fo) { *(f32x4*)(fo + n) = v0; *(f32x4*)(fo + n + 4) = v1; }
.LBB0_278:
	global_store_dwordx4 v[60:61], v[46:49], off
	global_store_dwordx4 v[60:61], v[42:45], off offset:16 nt

; DI unsigned pk2(float a, float b) { f32x2 v = {a, b}; bf16x2v r = __builtin_convertvector(v, bf16x2v); return __builtin_bit_cast(unsigned, r); }
;     DI void operator()(const f32x4 (&acc)[2][2][4][2], const pg8::Unit& u, int wr, int wc, int fr, int fq) const {
;     ...
;                 bf16_t* uo = p.u + (size_t)R * NU;
; #pragma unroll
;                 for (int bj = 0; bj < 2; ++bj) {
;                     const int n = colt + bj * 128 + wc * 32 + 8 * fq;
;                     f32x4 v0 = acc[ai][bj][m][0], v1 = acc[ai][bj][m][1];
;                     if (fo) { *(f32x4*)(fo + n) = v0; *(f32x4*)(fo + n + 4) = v1; }
;                     if (isq) { v0 = v0 * QSCALE; v1 = v1 * QSCALE; }
;                     else if (isg) {
; #pragma unroll
;                         for (int j = 0; j < 4; ++j) { v0[j] = v0[j] / (1.0f + __expf(-v0[j])); v1[j] = v1[j] / (1.0f + __expf(-v1[j])); }
;                     }
;                     *(u32x4*)(uo + n) = (u32x4){pk2(v0[0], v0[1]), pk2(v0[2], v0[3]), pk2(v1[0], v1[1]), pk2(v1[2], v1[3])};
.LBB0_285:
	v_ashrrev_i32_e32 v59, 31, v58
	v_lshlrev_b64 v[42:43], 13, v[58:59]
	v_lshl_add_u64 v[46:47], s[68:69], 0, v[42:43]
	v_cvt_pk_bf16_f32 v42, v50, v51
	v_cvt_pk_bf16_f32 v43, v52, v53
	v_cvt_pk_bf16_f32 v44, v54, v55
	v_cvt_pk_bf16_f32 v45, v56, v57
	v_lshl_add_u64 v[50:51], v[158:159], 1, v[46:47]
	global_store_dwordx4 v[50:51], v[42:45], off
	s_and_saveexec_b64 s[36:37], s[0:1]
	s_cbranch_execz .LBB0_287
	global_store_dwordx4 v[60:61], v[38:41], off offset:512 nt
	global_store_dwordx4 v[60:61], v[34:37], off offset:528 nt

;     DI void operator()(const f32x4 (&acc)[2][2][4][2], const pg8::Unit& u, int wr, int wc, int fr, int fq) const {
;     ...
;                 for (int bj = 0; bj < 2; ++bj) {
;                     const int n = colt + bj * 128 + wc * 32 + 8 * fq;
;                     f32x4 v0 = acc[ai][bj][m][0], v1 = acc[ai][bj][m][1];
;                     if (fo) { *(f32x4*)(fo + n) = v0; *(f32x4*)(fo + n + 4) = v1; }
.LBB0_302:
	global_store_dwordx4 v[44:45], v[30:33], off
	global_store_dwordx4 v[44:45], v[26:29], off offset:16 nt

; DI unsigned pk2(float a, float b) { f32x2 v = {a, b}; bf16x2v r = __builtin_convertvector(v, bf16x2v); return __builtin_bit_cast(unsigned, r); }
;     DI void operator()(const f32x4 (&acc)[2][2][4][2], const pg8::Unit& u, int wr, int wc, int fr, int fq) const {
;     ...
;                 bf16_t* uo = p.u + (size_t)R * NU;
; #pragma unroll
;                 for (int bj = 0; bj < 2; ++bj) {
;                     const int n = colt + bj * 128 + wc * 32 + 8 * fq;
;                     f32x4 v0 = acc[ai][bj][m][0], v1 = acc[ai][bj][m][1];
;                     if (fo) { *(f32x4*)(fo + n) = v0; *(f32x4*)(fo + n + 4) = v1; }
;                     if (isq) { v0 = v0 * QSCALE; v1 = v1 * QSCALE; }
;                     else if (isg) {
; #pragma unroll
;                         for (int j = 0; j < 4; ++j) { v0[j] = v0[j] / (1.0f + __expf(-v0[j])); v1[j] = v1[j] / (1.0f + __expf(-v1[j])); }
;                     }
;                     *(u32x4*)(uo + n) = (u32x4){pk2(v0[0], v0[1]), pk2(v0[2], v0[3]), pk2(v1[0], v1[1]), pk2(v1[2], v1[3])};
.LBB0_309:
	v_ashrrev_i32_e32 v43, 31, v42
	v_lshlrev_b64 v[26:27], 13, v[42:43]
	v_lshl_add_u64 v[30:31], s[68:69], 0, v[26:27]
	v_cvt_pk_bf16_f32 v26, v34, v35
	v_cvt_pk_bf16_f32 v27, v36, v37
	v_cvt_pk_bf16_f32 v28, v38, v39
	v_cvt_pk_bf16_f32 v29, v40, v41
	v_lshl_add_u64 v[34:35], v[158:159], 1, v[30:31]
	global_store_dwordx4 v[34:35], v[26:29], off
	s_and_saveexec_b64 s[36:37], s[0:1]
	s_cbranch_execz .LBB0_311
	global_store_dwordx4 v[44:45], v[22:25], off offset:512 nt
	global_store_dwordx4 v[44:45], v[18:21], off offset:528 nt

;     DI void operator()(const f32x4 (&acc)[2][2][4][2], const pg8::Unit& u, int wr, int wc, int fr, int fq) const {
;     ...
;                 for (int bj = 0; bj < 2; ++bj) {
;                     const int n = colt + bj * 128 + wc * 32 + 8 * fq;
;                     f32x4 v0 = acc[ai][bj][m][0], v1 = acc[ai][bj][m][1];
;                     if (fo) { *(f32x4*)(fo + n) = v0; *(f32x4*)(fo + n + 4) = v1; }
.LBB0_326:
	global_store_dwordx4 v[28:29], v[14:17], off
	global_store_dwordx4 v[28:29], v[10:13], off offset:16 nt

; DI unsigned pk2(float a, float b) { f32x2 v = {a, b}; bf16x2v r = __builtin_convertvector(v, bf16x2v); return __builtin_bit_cast(unsigned, r); }
;     DI void operator()(const f32x4 (&acc)[2][2][4][2], const pg8::Unit& u, int wr, int wc, int fr, int fq) const {
;     ...
;                 bf16_t* uo = p.u + (size_t)R * NU;
; #pragma unroll
;                 for (int bj = 0; bj < 2; ++bj) {
;                     const int n = colt + bj * 128 + wc * 32 + 8 * fq;
;                     f32x4 v0 = acc[ai][bj][m][0], v1 = acc[ai][bj][m][1];
;                     if (fo) { *(f32x4*)(fo + n) = v0; *(f32x4*)(fo + n + 4) = v1; }
;                     if (isq) { v0 = v0 * QSCALE; v1 = v1 * QSCALE; }
;                     else if (isg) {
; #pragma unroll
;                         for (int j = 0; j < 4; ++j) { v0[j] = v0[j] / (1.0f + __expf(-v0[j])); v1[j] = v1[j] / (1.0f + __expf(-v1[j])); }
;                     }
;                     *(u32x4*)(uo + n) = (u32x4){pk2(v0[0], v0[1]), pk2(v0[2], v0[3]), pk2(v1[0], v1[1]), pk2(v1[2], v1[3])};
.LBB0_333:
	v_ashrrev_i32_e32 v27, 31, v26
	v_lshlrev_b64 v[10:11], 13, v[26:27]
	v_lshl_add_u64 v[14:15], s[68:69], 0, v[10:11]
	v_cvt_pk_bf16_f32 v10, v18, v19
	v_cvt_pk_bf16_f32 v11, v20, v21
	v_cvt_pk_bf16_f32 v12, v22, v23
	v_cvt_pk_bf16_f32 v13, v24, v25
	v_lshl_add_u64 v[18:19], v[158:159], 1, v[14:15]
	global_store_dwordx4 v[18:19], v[10:13], off
	s_and_saveexec_b64 s[10:11], s[0:1]
	s_cbranch_execz .LBB0_335
	global_store_dwordx4 v[28:29], v[6:9], off offset:512 nt
	global_store_dwordx4 v[28:29], v[2:5], off offset:528 nt

;     DI void operator()(const f32x4 (&acc)[2][2][4][2], const pg8::Unit& u, int wr, int wc, int fr, int fq) const {
;     ...
;                 for (int bj = 0; bj < 2; ++bj) {
;                     const int n = colt + bj * 128 + wc * 32 + 8 * fq;
;                     f32x4 v0 = acc[ai][bj][m][0], v1 = acc[ai][bj][m][1];
;                     if (fo) { *(f32x4*)(fo + n) = v0; *(f32x4*)(fo + n + 4) = v1; }
.Lp1q_kvst_0_0:
	global_store_dwordx4 v188, v[126:129], s[8:9]
	global_store_dwordx4 v188, v[122:125], s[8:9] offset:16 nt

;     DI void operator()(const f32x4 (&acc)[2][2][4][2], const pg8::Unit& u, int wr, int wc, int fr, int fq) const {
;     ...
;                 for (int bj = 0; bj < 2; ++bj) {
;                     const int n = colt + bj * 128 + wc * 32 + 8 * fq;
;                     f32x4 v0 = acc[ai][bj][m][0], v1 = acc[ai][bj][m][1];
;                     if (fo) { *(f32x4*)(fo + n) = v0; *(f32x4*)(fo + n + 4) = v1; }
.Lp1q_kvst_0_1:
	global_store_dwordx4 v188, v[110:113], s[8:9]
	global_store_dwordx4 v188, v[106:109], s[8:9] offset:16 nt

;     DI void operator()(const f32x4 (&acc)[2][2][4][2], const pg8::Unit& u, int wr, int wc, int fr, int fq) const {
;     ...
;                 for (int bj = 0; bj < 2; ++bj) {
;                     const int n = colt + bj * 128 + wc * 32 + 8 * fq;
;                     f32x4 v0 = acc[ai][bj][m][0], v1 = acc[ai][bj][m][1];
;                     if (fo) { *(f32x4*)(fo + n) = v0; *(f32x4*)(fo + n + 4) = v1; }
.Lp1q_kvst_0_2:
	global_store_dwordx4 v188, v[94:97], s[8:9]
	global_store_dwordx4 v188, v[90:93], s[8:9] offset:16 nt

;     DI void operator()(const f32x4 (&acc)[2][2][4][2], const pg8::Unit& u, int wr, int wc, int fr, int fq) const {
;     ...
;                 for (int bj = 0; bj < 2; ++bj) {
;                     const int n = colt + bj * 128 + wc * 32 + 8 * fq;
;                     f32x4 v0 = acc[ai][bj][m][0], v1 = acc[ai][bj][m][1];
;                     if (fo) { *(f32x4*)(fo + n) = v0; *(f32x4*)(fo + n + 4) = v1; }
.Lp1q_kvst_0_3:
	global_store_dwordx4 v188, v[78:81], s[8:9]
	global_store_dwordx4 v188, v[74:77], s[8:9] offset:16 nt

;     DI void operator()(const f32x4 (&acc)[2][2][4][2], const pg8::Unit& u, int wr, int wc, int fr, int fq) const {
;     ...
;                 for (int bj = 0; bj < 2; ++bj) {
;                     const int n = colt + bj * 128 + wc * 32 + 8 * fq;
;                     f32x4 v0 = acc[ai][bj][m][0], v1 = acc[ai][bj][m][1];
;                     if (fo) { *(f32x4*)(fo + n) = v0; *(f32x4*)(fo + n + 4) = v1; }
.Lp1q_kvst_1_0:
	global_store_dwordx4 v188, v[118:121], s[8:9] offset:512 nt
	global_store_dwordx4 v188, v[114:117], s[8:9] offset:528 nt

;     DI void operator()(const f32x4 (&acc)[2][2][4][2], const pg8::Unit& u, int wr, int wc, int fr, int fq) const {
;     ...
;                 for (int bj = 0; bj < 2; ++bj) {
;                     const int n = colt + bj * 128 + wc * 32 + 8 * fq;
;                     f32x4 v0 = acc[ai][bj][m][0], v1 = acc[ai][bj][m][1];
;                     if (fo) { *(f32x4*)(fo + n) = v0; *(f32x4*)(fo + n + 4) = v1; }
.Lp1q_kvst_1_1:
	global_store_dwordx4 v188, v[102:105], s[8:9] offset:512 nt
	global_store_dwordx4 v188, v[98:101], s[8:9] offset:528 nt

;     DI void operator()(const f32x4 (&acc)[2][2][4][2], const pg8::Unit& u, int wr, int wc, int fr, int fq) const {
;     ...
;                 for (int bj = 0; bj < 2; ++bj) {
;                     const int n = colt + bj * 128 + wc * 32 + 8 * fq;
;                     f32x4 v0 = acc[ai][bj][m][0], v1 = acc[ai][bj][m][1];
;                     if (fo) { *(f32x4*)(fo + n) = v0; *(f32x4*)(fo + n + 4) = v1; }
.Lp1q_kvst_1_2:
	global_store_dwordx4 v188, v[86:89], s[8:9] offset:512 nt
	global_store_dwordx4 v188, v[82:85], s[8:9] offset:528 nt

;     DI void operator()(const f32x4 (&acc)[2][2][4][2], const pg8::Unit& u, int wr, int wc, int fr, int fq) const {
;     ...
;                 for (int bj = 0; bj < 2; ++bj) {
;                     const int n = colt + bj * 128 + wc * 32 + 8 * fq;
;                     f32x4 v0 = acc[ai][bj][m][0], v1 = acc[ai][bj][m][1];
;                     if (fo) { *(f32x4*)(fo + n) = v0; *(f32x4*)(fo + n + 4) = v1; }
.Lp1q_kvst_1_3:
	global_store_dwordx4 v188, v[70:73], s[8:9] offset:512 nt
	global_store_dwordx4 v188, v[66:69], s[8:9] offset:528 nt

;     DI void operator()(const f32x4 (&acc)[2][2][4][2], const pg8::Unit& u, int wr, int wc, int fr, int fq) const {
;     ...
;                 for (int bj = 0; bj < 2; ++bj) {
;                     const int n = colt + bj * 128 + wc * 32 + 8 * fq;
;                     f32x4 v0 = acc[ai][bj][m][0], v1 = acc[ai][bj][m][1];
;                     if (fo) { *(f32x4*)(fo + n) = v0; *(f32x4*)(fo + n + 4) = v1; }
.Lp1q_kvst_2_0:
	global_store_dwordx4 v188, v[62:65], s[8:9]
	global_store_dwordx4 v188, v[58:61], s[8:9] offset:16 nt

;     DI void operator()(const f32x4 (&acc)[2][2][4][2], const pg8::Unit& u, int wr, int wc, int fr, int fq) const {
;     ...
;                 for (int bj = 0; bj < 2; ++bj) {
;                     const int n = colt + bj * 128 + wc * 32 + 8 * fq;
;                     f32x4 v0 = acc[ai][bj][m][0], v1 = acc[ai][bj][m][1];
;                     if (fo) { *(f32x4*)(fo + n) = v0; *(f32x4*)(fo + n + 4) = v1; }
.Lp1q_kvst_2_1:
	global_store_dwordx4 v188, v[46:49], s[8:9]
	global_store_dwordx4 v188, v[42:45], s[8:9] offset:16 nt

;     DI void operator()(const f32x4 (&acc)[2][2][4][2], const pg8::Unit& u, int wr, int wc, int fr, int fq) const {
;     ...
;                 for (int bj = 0; bj < 2; ++bj) {
;                     const int n = colt + bj * 128 + wc * 32 + 8 * fq;
;                     f32x4 v0 = acc[ai][bj][m][0], v1 = acc[ai][bj][m][1];
;                     if (fo) { *(f32x4*)(fo + n) = v0; *(f32x4*)(fo + n + 4) = v1; }
.Lp1q_kvst_2_2:
	global_store_dwordx4 v188, v[30:33], s[8:9]
	global_store_dwordx4 v188, v[26:29], s[8:9] offset:16 nt

;     DI void operator()(const f32x4 (&acc)[2][2][4][2], const pg8::Unit& u, int wr, int wc, int fr, int fq) const {
;     ...
;                 for (int bj = 0; bj < 2; ++bj) {
;                     const int n = colt + bj * 128 + wc * 32 + 8 * fq;
;                     f32x4 v0 = acc[ai][bj][m][0], v1 = acc[ai][bj][m][1];
;                     if (fo) { *(f32x4*)(fo + n) = v0; *(f32x4*)(fo + n + 4) = v1; }
.Lp1q_kvst_2_3:
	global_store_dwordx4 v188, v[14:17], s[8:9]
	global_store_dwordx4 v188, v[10:13], s[8:9] offset:16 nt

;     DI void operator()(const f32x4 (&acc)[2][2][4][2], const pg8::Unit& u, int wr, int wc, int fr, int fq) const {
;     ...
;                 for (int bj = 0; bj < 2; ++bj) {
;                     const int n = colt + bj * 128 + wc * 32 + 8 * fq;
;                     f32x4 v0 = acc[ai][bj][m][0], v1 = acc[ai][bj][m][1];
;                     if (fo) { *(f32x4*)(fo + n) = v0; *(f32x4*)(fo + n + 4) = v1; }
.Lp1q_kvst_3_0:
	global_store_dwordx4 v188, v[54:57], s[8:9] offset:512 nt
	global_store_dwordx4 v188, v[50:53], s[8:9] offset:528 nt

;     DI void operator()(const f32x4 (&acc)[2][2][4][2], const pg8::Unit& u, int wr, int wc, int fr, int fq) const {
;     ...
;                 for (int bj = 0; bj < 2; ++bj) {
;                     const int n = colt + bj * 128 + wc * 32 + 8 * fq;
;                     f32x4 v0 = acc[ai][bj][m][0], v1 = acc[ai][bj][m][1];
;                     if (fo) { *(f32x4*)(fo + n) = v0; *(f32x4*)(fo + n + 4) = v1; }
.Lp1q_kvst_3_1:
	global_store_dwordx4 v188, v[38:41], s[8:9] offset:512 nt
	global_store_dwordx4 v188, v[34:37], s[8:9] offset:528 nt

;     DI void operator()(const f32x4 (&acc)[2][2][4][2], const pg8::Unit& u, int wr, int wc, int fr, int fq) const {
;     ...
;                 for (int bj = 0; bj < 2; ++bj) {
;                     const int n = colt + bj * 128 + wc * 32 + 8 * fq;
;                     f32x4 v0 = acc[ai][bj][m][0], v1 = acc[ai][bj][m][1];
;                     if (fo) { *(f32x4*)(fo + n) = v0; *(f32x4*)(fo + n + 4) = v1; }
.Lp1q_kvst_3_2:
	global_store_dwordx4 v188, v[22:25], s[8:9] offset:512 nt
	global_store_dwordx4 v188, v[18:21], s[8:9] offset:528 nt

;     DI void operator()(const f32x4 (&acc)[2][2][4][2], const pg8::Unit& u, int wr, int wc, int fr, int fq) const {
;     ...
;                 for (int bj = 0; bj < 2; ++bj) {
;                     const int n = colt + bj * 128 + wc * 32 + 8 * fq;
;                     f32x4 v0 = acc[ai][bj][m][0], v1 = acc[ai][bj][m][1];
;                     if (fo) { *(f32x4*)(fo + n) = v0; *(f32x4*)(fo + n + 4) = v1; }
.Lp1q_kvst_3_3:
	global_store_dwordx4 v188, v[6:9], s[8:9] offset:512 nt
	global_store_dwordx4 v188, v[2:5], s[8:9] offset:528 nt
